# early per-WG buffer_wbl2 before grid barriers 2 and 3
# baseline (speedup 1.0000x reference)
.Lp1a_after:
	s_cmp_gt_i32 s71, 2
	s_cbranch_scc0 .LBB0_278
	s_lshr_b32 s32, s79, 6
	s_cmp_lg_u32 s32, 0
	s_cbranch_scc1 .Lewb2
	buffer_wbl2 sc1
.Lewb2:
	s_waitcnt vmcnt(0)
	s_waitcnt vmcnt(0) lgkmcnt(0)
	s_barrier
	s_and_saveexec_b64 s[0:1], s[82:83]
	s_cbranch_execz .LBB0_277
	s_add_i32 s3, 0, 0x20020
	v_mov_b32_e32 v0, s3
	s_waitcnt vmcnt(0) expcnt(0) lgkmcnt(0)
	ds_read_b32 v2, v0
	s_add_i32 s3, 0, 0x20024
	v_mov_b32_e32 v0, s3
	ds_read_b32 v0, v0
	s_waitcnt lgkmcnt(1)
	v_cmp_ne_u32_e32 vcc, 0, v2
	s_cbranch_vccnz .LBB0_241
	s_add_u32 s4, s68, 0x40200
	s_addc_u32 s5, s69, 0
	s_add_u32 s6, s68, 0x40400
	s_addc_u32 s7, s69, 0
	s_add_u32 s8, s68, 0x40500
	s_addc_u32 s9, s69, 0
	s_add_u32 s10, s68, 0x40600
	s_addc_u32 s11, s69, 0
	s_add_u32 s12, s68, 0x40700
	s_addc_u32 s13, s69, 0
	s_add_u32 s14, s68, 0x40800
	s_addc_u32 s15, s69, 0
	s_add_u32 s16, s68, 0x40900
	s_addc_u32 s17, s69, 0
	s_add_u32 s18, s68, 0x40a00
	s_addc_u32 s19, s69, 0
	s_add_u32 s20, s68, 0x40b00
	s_addc_u32 s21, s69, 0
	s_add_u32 s22, s68, 0x40c00
	s_addc_u32 s23, s69, 0
	s_add_u32 s24, s68, 0x40d00
	s_addc_u32 s25, s69, 0
	s_add_u32 s26, s68, 0x40e00
	s_addc_u32 s27, s69, 0
	s_add_u32 s28, s68, 0x40f00
	s_addc_u32 s29, s69, 0
	s_add_u32 s30, s68, 0x41000
	s_addc_u32 s31, s69, 0
	s_add_u32 s34, s68, 0x41100
	s_addc_u32 s35, s69, 0
	s_add_u32 s36, s68, 0x41200
	s_addc_u32 s37, s69, 0
	s_mul_i32 s3, s87, s78
	s_add_u32 s38, s68, 0x41300
	s_mul_i32 s3, s3, s86
	s_addc_u32 s39, s69, 0
	s_mov_b32 s33, 1
	v_mov_b32_e32 v16, 0
	s_branch .LBB0_229

.LBB0_381:
	s_lshr_b32 s32, s79, 6
	s_cmp_lg_u32 s32, 0
	s_cbranch_scc1 .Lewb3
	buffer_wbl2 sc1
